# speedup vs baseline: 1.0028x; 1.0005x over previous
; DI float h2lo(unsigned u) { return (float)__builtin_bit_cast(f16x2_t, u)[0]; }
; DI float h2hi(unsigned u) { return (float)__builtin_bit_cast(f16x2_t, u)[1]; }
; DI float shfl_xor_l(float v, int mask, int lane) { return __int_as_float(__builtin_amdgcn_ds_bpermute((lane ^ mask) << 2, __float_as_int(v))); }
; DI void ln_phase(const Params& p, const u16* src, const float* g, const float* b, float* dstf, u16* dstb) {
;     ...
;     for (int i = 0; i < 4; ++i) { v[i] = (f32x4){h2lo(raw[i][0]), h2hi(raw[i][0]), h2lo(raw[i][1]), h2hi(raw[i][1])}; s += (v[i][0] + v[i][1]) + (v[i][2] + v[i][3]); }
; #pragma unroll
;     for (int o = 32; o >= 1; o >>= 1) s += shfl_xor_l(s, o, lane);
;     const float mu = s * (1.0f / 1024.0f);
;     float q = 0.f;
; #pragma unroll
;     for (int i = 0; i < 4; ++i) { v[i] = v[i] - mu; q += (v[i][0] * v[i][0] + v[i][1] * v[i][1]) + (v[i][2] * v[i][2] + v[i][3] * v[i][3]); }
; #pragma unroll
;     for (int o = 32; o >= 1; o >>= 1) q += shfl_xor_l(q, o, lane);
;     const float rstd = 1.0f / sqrtf(q * (1.0f / 1024.0f) + 1e-5f);
; #pragma unroll
;     for (int i = 0; i < 4; ++i) {
;       const int col = i * 256 + lane * 4;
;       const f32x4 o = v[i] * rstd * gv[i] + bv[i];
;       if (dstf) *(f32x4*)(dstf + (size_t)row * D + col) = o;
.LBB0_1327:
	s_or_b64 exec, exec, s[38:39]
	s_waitcnt vmcnt(3)
	v_cvt_f32_f16_sdwa v56, v54 dst_sel:DWORD dst_unused:UNUSED_PAD src0_sel:WORD_1
	v_cvt_f32_f16_e32 v58, v54
	v_cvt_f32_f16_sdwa v57, v55 dst_sel:DWORD dst_unused:UNUSED_PAD src0_sel:WORD_1
	v_cvt_f32_f16_e32 v59, v55
	s_waitcnt vmcnt(2)
	v_cvt_f32_f16_sdwa v60, v52 dst_sel:DWORD dst_unused:UNUSED_PAD src0_sel:WORD_1
	v_cvt_f32_f16_e32 v62, v52
	v_cvt_f32_f16_sdwa v61, v53 dst_sel:DWORD dst_unused:UNUSED_PAD src0_sel:WORD_1
	v_cvt_f32_f16_e32 v63, v53
	v_pk_add_f32 v[56:57], v[58:59], v[56:57]
	s_waitcnt vmcnt(1)
	v_cvt_f32_f16_sdwa v66, v35 dst_sel:DWORD dst_unused:UNUSED_PAD src0_sel:WORD_1
	v_add_f32_e32 v37, v56, v57
	v_pk_add_f32 v[58:59], v[62:63], v[60:61]
	v_add_f32_e32 v57, 0, v37
	v_pk_add_f32 v[58:59], v[58:59], v[58:59] op_sel_hi:[0,1]
	v_cvt_f32_f16_sdwa v37, v34 dst_sel:DWORD dst_unused:UNUSED_PAD src0_sel:WORD_1
	v_cvt_f32_f16_e32 v61, v34
	v_cvt_f32_f16_e32 v67, v35
	s_waitcnt vmcnt(0)
	v_cvt_f32_f16_sdwa v60, v32 dst_sel:DWORD dst_unused:UNUSED_PAD src0_sel:WORD_1
	v_cvt_f32_f16_e32 v62, v32
	v_cvt_f32_f16_sdwa v56, v33 dst_sel:DWORD dst_unused:UNUSED_PAD src0_sel:WORD_1
	v_cvt_f32_f16_e32 v58, v33
	v_add_f32_e32 v63, v61, v37
	v_add_f32_e32 v61, v67, v66
	v_pk_add_f32 v[60:61], v[62:63], v[60:61]
	v_pk_add_f32 v[56:57], v[58:59], v[56:57]
	s_nop 0
	v_pk_add_f32 v[56:57], v[60:61], v[56:57]
	s_nop 0
	v_add_f32_e32 v37, v56, v57
	s_nop 1
	v_add_f32_dpp v37, v37, v37 quad_perm:[1,0,3,2] row_mask:0xf bank_mask:0xf
	s_nop 1
	v_add_f32_dpp v37, v37, v37 quad_perm:[2,3,0,1] row_mask:0xf bank_mask:0xf
	s_nop 1
	v_add_f32_dpp v37, v37, v37 row_half_mirror row_mask:0xf bank_mask:0xf
	s_nop 1
	v_add_f32_dpp v37, v37, v37 row_mirror row_mask:0xf bank_mask:0xf
	v_mov_b32_e32 v56, v37
	s_nop 1
	v_permlane16_swap_b32 v56, v37
	v_add_f32_e32 v37, v37, v56
	v_mov_b32_e32 v56, v37
	s_nop 1
	v_permlane32_swap_b32 v56, v37
	v_add_f32_e32 v37, v37, v56
	v_fma_mix_f32 v67, v37, s65, v54 op_sel:[0,0,1] op_sel_hi:[0,0,1]
	v_fma_mix_f32 v66, v37, s65, v54 op_sel_hi:[0,0,1]
	v_fma_mix_f32 v77, v37, s65, v55 op_sel:[0,0,1] op_sel_hi:[0,0,1]
	v_fma_mix_f32 v76, v37, s65, v55 op_sel_hi:[0,0,1]
	v_fma_mix_f32 v61, v37, s65, v53 op_sel:[0,0,1] op_sel_hi:[0,0,1]
	v_fma_mix_f32 v60, v37, s65, v53 op_sel_hi:[0,0,1]
	v_fma_mix_f32 v63, v37, s65, v52 op_sel:[0,0,1] op_sel_hi:[0,0,1]
	v_fma_mix_f32 v62, v37, s65, v52 op_sel_hi:[0,0,1]
	v_pk_mul_f32 v[52:53], v[76:77], v[76:77]
	v_pk_mul_f32 v[54:55], v[66:67], v[66:67]
	v_pk_mul_f32 v[56:57], v[60:61], v[60:61]
	v_pk_mov_b32 v[58:59], v[54:55], v[52:53] op_sel:[1,0]
	v_mov_b32_e32 v55, v53
	v_pk_add_f32 v[52:53], v[58:59], v[54:55]
	v_fma_mix_f32 v58, v37, s65, v34 op_sel_hi:[0,0,1]
	v_pk_add_f32 v[68:69], v[52:53], v[52:53] op_sel_hi:[0,1]
	v_pk_mul_f32 v[52:53], v[62:63], v[62:63]
	v_fma_mix_f32 v59, v37, s65, v34 op_sel:[0,0,1] op_sel_hi:[0,0,1]
	v_mul_f32_e32 v34, v58, v58
	v_pk_mov_b32 v[54:55], v[52:53], v[56:57] op_sel:[1,0]
	v_mov_b32_e32 v53, v57
	v_fma_mix_f32 v57, v37, s65, v35 op_sel:[0,0,1] op_sel_hi:[0,0,1]
	v_fma_mix_f32 v56, v37, s65, v35 op_sel_hi:[0,0,1]
	v_pk_fma_f32 v[34:35], v[58:59], v[58:59], v[34:35] op_sel_hi:[1,1,0]
	v_pk_add_f32 v[52:53], v[54:55], v[52:53]
	v_mul_f32_e32 v34, v56, v56
	v_pk_add_f32 v[78:79], v[52:53], v[52:53] op_sel_hi:[0,1]
	v_pk_fma_f32 v[80:81], v[56:57], v[56:57], v[34:35] op_sel_hi:[1,1,0]
	v_fma_mix_f32 v53, v37, s65, v33 op_sel:[0,0,1] op_sel_hi:[0,0,1]
	v_fma_mix_f32 v52, v37, s65, v33 op_sel_hi:[0,0,1]
	v_fma_mix_f32 v55, v37, s65, v32 op_sel:[0,0,1] op_sel_hi:[0,0,1]
	v_fma_mix_f32 v54, v37, s65, v32 op_sel_hi:[0,0,1]
	v_mul_f32_e32 v34, v54, v54
	v_mul_f32_e32 v80, v55, v55
	v_mul_f32_e32 v68, v52, v52
	v_mul_f32_e32 v78, v53, v53
	v_pk_add_f32 v[32:33], v[34:35], v[80:81]
	v_pk_add_f32 v[34:35], v[68:69], v[78:79]
	s_nop 0
	v_pk_add_f32 v[32:33], v[32:33], v[34:35]
	s_nop 0
	v_add_f32_e32 v32, v32, v33
	s_nop 1
	v_add_f32_dpp v32, v32, v32 quad_perm:[1,0,3,2] row_mask:0xf bank_mask:0xf
	s_nop 1
	v_add_f32_dpp v32, v32, v32 quad_perm:[2,3,0,1] row_mask:0xf bank_mask:0xf
	s_nop 1
	v_add_f32_dpp v32, v32, v32 row_half_mirror row_mask:0xf bank_mask:0xf
	s_nop 1
	v_add_f32_dpp v32, v32, v32 row_mirror row_mask:0xf bank_mask:0xf
	v_mov_b32_e32 v33, v32
	s_nop 1
	v_permlane16_swap_b32 v33, v32
	v_add_f32_e32 v32, v32, v33
	v_mov_b32_e32 v33, v32
	s_nop 1
	v_permlane32_swap_b32 v33, v32
	v_add_f32_e32 v32, v32, v33
	v_mov_b32_e32 v33, 0x3727c5ac
	v_fmamk_f32 v32, v32, 0x3a800000, v33
	v_mul_f32_e32 v33, 0x4f800000, v32
	v_cmp_gt_f32_e32 vcc, s66, v32
	s_nop 1
	v_cndmask_b32_e32 v32, v32, v33, vcc
	v_sqrt_f32_e32 v33, v32
	s_nop 0
	v_add_u32_e32 v34, -1, v33
	v_add_u32_e32 v35, 1, v33
	v_fma_f32 v37, -v34, v33, v32
	v_fma_f32 v68, -v35, v33, v32
	v_cmp_ge_f32_e64 s[38:39], 0, v37
	s_nop 1
	v_cndmask_b32_e64 v33, v33, v34, s[38:39]
	v_cmp_lt_f32_e64 s[38:39], 0, v68
	s_nop 1
	v_cndmask_b32_e64 v33, v33, v35, s[38:39]
	v_mul_f32_e32 v34, 0x37800000, v33
	v_cndmask_b32_e32 v33, v33, v34, vcc
	v_mov_b32_e32 v34, 0x260
	v_cmp_class_f32_e32 vcc, v32, v34
	s_nop 1
	v_cndmask_b32_e32 v32, v33, v32, vcc
	v_div_scale_f32 v33, s[2:3], v32, v32, 1.0
	v_rcp_f32_e32 v34, v33
	v_div_scale_f32 v35, vcc, 1.0, v32, 1.0
	v_fma_f32 v37, -v33, v34, 1.0
	v_fmac_f32_e32 v34, v37, v34
	v_mul_f32_e32 v37, v35, v34
	v_fma_f32 v68, -v33, v37, v35
	v_fmac_f32_e32 v37, v68, v34
	v_fma_f32 v33, -v33, v37, v35
	v_div_fmas_f32 v33, v33, v34, v37
	v_div_fixup_f32 v68, v33, v32, 1.0
	v_pk_mul_f32 v[32:33], v[66:67], v[68:69] op_sel_hi:[1,0]
	v_pk_mul_f32 v[34:35], v[76:77], v[68:69] op_sel_hi:[1,0]
	v_cndmask_b32_e64 v37, 0, 1, s[28:29]
	v_pk_fma_f32 v[34:35], v[2:3], v[34:35], v[10:11]
	v_cmp_ne_u32_e64 s[38:39], 1, v37
	s_andn2_b64 vcc, exec, s[28:29]
	v_pk_fma_f32 v[32:33], v[0:1], v[32:33], v[8:9]
	s_cbranch_vccnz .LBB0_1329
	global_store_dwordx4 v[42:43], v[32:35], off offset:-2048 sc0 sc1

; DI void ln_phase(const Params& p, const u16* src, const float* g, const float* b, float* dstf, u16* dstb) {
;     ...
;     for (int i = 0; i < 4; ++i) {
;       const int col = i * 256 + lane * 4;
;       const f32x4 o = v[i] * rstd * gv[i] + bv[i];
;       if (dstf) *(f32x4*)(dstf + (size_t)row * D + col) = o;
.LBB0_1331:
	v_mov_b32_e32 v69, v68
	v_mov_b32_e32 v32, v68
	v_mov_b32_e32 v33, v68
	v_pk_mul_f32 v[32:33], v[60:61], v[32:33]
	v_pk_mul_f32 v[60:61], v[62:63], v[68:69]
	v_pk_fma_f32 v[34:35], v[6:7], v[32:33], v[14:15]
	s_and_b64 vcc, exec, s[38:39]
	v_pk_fma_f32 v[32:33], v[4:5], v[60:61], v[12:13]
	s_cbranch_vccnz .LBB0_1333
	global_store_dwordx4 v[42:43], v[32:35], off offset:-1024 sc0 sc1

; DI void ln_phase(const Params& p, const u16* src, const float* g, const float* b, float* dstf, u16* dstb) {
;     ...
;     for (int i = 0; i < 4; ++i) {
;       const int col = i * 256 + lane * 4;
;       const f32x4 o = v[i] * rstd * gv[i] + bv[i];
;       if (dstf) *(f32x4*)(dstf + (size_t)row * D + col) = o;
.LBB0_1335:
	v_mov_b32_e32 v32, v68
	v_mov_b32_e32 v33, v68
	v_pk_mul_f32 v[32:33], v[56:57], v[32:33]
	v_pk_mul_f32 v[56:57], v[58:59], v[68:69]
	v_pk_fma_f32 v[34:35], v[18:19], v[32:33], v[26:27]
	s_and_b64 vcc, exec, s[38:39]
	v_pk_fma_f32 v[32:33], v[16:17], v[56:57], v[24:25]
	s_cbranch_vccnz .LBB0_1337
	global_store_dwordx4 v[42:43], v[32:35], off sc0 sc1

; DI void ln_phase(const Params& p, const u16* src, const float* g, const float* b, float* dstf, u16* dstb) {
;     ...
;     for (int i = 0; i < 4; ++i) {
;       const int col = i * 256 + lane * 4;
;       const f32x4 o = v[i] * rstd * gv[i] + bv[i];
;       if (dstf) *(f32x4*)(dstf + (size_t)row * D + col) = o;
.LBB0_1339:
	v_mov_b32_e32 v32, v68
	v_mov_b32_e32 v33, v68
	v_pk_mul_f32 v[32:33], v[52:53], v[32:33]
	v_pk_mul_f32 v[52:53], v[54:55], v[68:69]
	v_pk_fma_f32 v[34:35], v[22:23], v[32:33], v[30:31]
	s_and_b64 vcc, exec, s[38:39]
	v_pk_fma_f32 v[32:33], v[20:21], v[52:53], v[28:29]
	s_cbranch_vccnz .LBB0_1341
	global_store_dwordx4 v[42:43], v[32:35], off offset:1024 sc0 sc1
